# attention epilogues (FoX and SWA): permlane32_swap pairs then 8 dwordx4 stores per lane instead of 16 dwordx2
# speedup vs baseline: 1.0085x; 1.0068x over previous
; template <bool FOX> ...
;     ...
; #pragma unroll
;   for (int qt = 0; qt < 2; ++qt) {
;     float lt = xsum32(lrun[qt]);
;     float inv = 1.f / lt;
;     u16* yp = Yb + (size_t)(q0 + qt * 32 + ln) * ldy;
; #pragma unroll
;     for (int dt = 0; dt < 2; ++dt)
; #pragma unroll
;       for (int jj = 0; jj < 4; ++jj) {
;         uint2 pk;
;         pk.x = pack2(o[dt][qt][4 * jj + 0] * inv, o[dt][qt][4 * jj + 1] * inv);
;         pk.y = pack2(o[dt][qt][4 * jj + 2] * inv, o[dt][qt][4 * jj + 3] * inv);
;         *reinterpret_cast<uint2*>(yp + dt * 32 + 8 * jj + 4 * hh) = pk;
;       }
;   }
.LBB0_496:
	s_lshl_b64 s[0:1], s[4:5], 23
	s_add_u32 s0, s30, s0
	s_addc_u32 s1, s31, s1
	s_lshl_b32 s4, s9, 1
	s_add_u32 s0, s0, s4
	s_addc_u32 s1, s1, 0
	v_mov_b32_e32 v66, v64
	v_mov_b32_e32 v67, v164
	v_ashrrev_i32_e32 v169, 31, v168
	s_nop 0
	v_permlane32_swap_b32_e32 v64, v66
	v_permlane32_swap_b32_e32 v164, v67
	v_add_f32_e32 v66, v64, v66
	v_add_f32_e32 v67, v164, v67
	v_lshl_add_u64 v[64:65], v[168:169], 1, s[0:1]
	v_div_scale_f32 v80, s[4:5], v66, v66, 1.0
	v_rcp_f32_e32 v81, v80
	v_div_scale_f32 v82, vcc, 1.0, v66, 1.0
	v_fma_f32 v83, -v80, v81, 1.0
	v_fmac_f32_e32 v81, v83, v81
	v_mul_f32_e32 v83, v82, v81
	v_fma_f32 v84, -v80, v83, v82
	v_fmac_f32_e32 v83, v84, v81
	v_fma_f32 v80, -v80, v83, v82
	v_div_fmas_f32 v80, v80, v81, v83
	v_div_fixup_f32 v68, v80, v66, 1.0
	v_div_scale_f32 v86, s[4:5], v67, v67, 1.0
	v_rcp_f32_e32 v87, v86
	v_div_scale_f32 v88, vcc, 1.0, v67, 1.0
	v_fma_f32 v89, -v86, v87, 1.0
	v_fmac_f32_e32 v87, v89, v87
	v_mul_f32_e32 v89, v88, v87
	v_fma_f32 v90, -v86, v89, v88
	v_fmac_f32_e32 v89, v90, v87
	v_fma_f32 v86, -v86, v89, v88
	v_div_fmas_f32 v86, v86, v87, v89
	v_div_fixup_f32 v70, v86, v67, 1.0
	v_mbcnt_lo_u32_b32 v74, -1, 0
	v_mbcnt_hi_u32_b32 v74, -1, v74
	v_and_b32_e32 v74, 32, v74
	v_lshrrev_b32_e32 v74, 2, v74
	v_mov_b32_e32 v75, 0
	v_lshlrev_b64 v[76:77], 11, v[166:167]
	v_lshlrev_b64 v[78:79], 11, v[162:163]
	v_lshl_add_u64 v[76:77], v[64:65], 0, v[76:77]
	v_lshl_add_u64 v[78:79], v[64:65], 0, v[78:79]
	v_lshl_add_u64 v[76:77], v[76:77], 0, v[74:75]
	v_lshl_add_u64 v[78:79], v[78:79], 0, v[74:75]
	v_mul_f32_e32 v48, v48, v68
	v_mul_f32_e32 v49, v49, v68
	v_mul_f32_e32 v50, v50, v68
	v_mul_f32_e32 v51, v51, v68
	v_mul_f32_e32 v52, v52, v68
	v_mul_f32_e32 v53, v53, v68
	v_mul_f32_e32 v54, v54, v68
	v_mul_f32_e32 v55, v55, v68
	v_cvt_pk_bf16_f32 v48, v48, v49
	v_cvt_pk_bf16_f32 v49, v50, v51
	v_cvt_pk_bf16_f32 v50, v52, v53
	v_cvt_pk_bf16_f32 v51, v54, v55
	s_nop 1
	v_permlane32_swap_b32_e32 v48, v50
	v_permlane32_swap_b32_e32 v49, v51
	global_store_dwordx4 v[76:77], v[48:51], off
	v_mul_f32_e32 v56, v56, v68
	v_mul_f32_e32 v57, v57, v68
	v_mul_f32_e32 v58, v58, v68
	v_mul_f32_e32 v59, v59, v68
	v_mul_f32_e32 v60, v60, v68
	v_mul_f32_e32 v61, v61, v68
	v_mul_f32_e32 v62, v62, v68
	v_mul_f32_e32 v63, v63, v68
	v_cvt_pk_bf16_f32 v56, v56, v57
	v_cvt_pk_bf16_f32 v57, v58, v59
	v_cvt_pk_bf16_f32 v58, v60, v61
	v_cvt_pk_bf16_f32 v59, v62, v63
	s_nop 1
	v_permlane32_swap_b32_e32 v56, v58
	v_permlane32_swap_b32_e32 v57, v59
	global_store_dwordx4 v[76:77], v[56:59], off offset:32
	v_mul_f32_e32 v32, v32, v68
	v_mul_f32_e32 v33, v33, v68
	v_mul_f32_e32 v34, v34, v68
	v_mul_f32_e32 v35, v35, v68
	v_mul_f32_e32 v36, v36, v68
	v_mul_f32_e32 v37, v37, v68
	v_mul_f32_e32 v38, v38, v68
	v_mul_f32_e32 v39, v39, v68
	v_cvt_pk_bf16_f32 v32, v32, v33
	v_cvt_pk_bf16_f32 v33, v34, v35
	v_cvt_pk_bf16_f32 v34, v36, v37
	v_cvt_pk_bf16_f32 v35, v38, v39
	s_nop 1
	v_permlane32_swap_b32_e32 v32, v34
	v_permlane32_swap_b32_e32 v33, v35
	global_store_dwordx4 v[76:77], v[32:35], off offset:64
	v_mul_f32_e32 v40, v40, v68
	v_mul_f32_e32 v41, v41, v68
	v_mul_f32_e32 v42, v42, v68
	v_mul_f32_e32 v43, v43, v68
	v_mul_f32_e32 v44, v44, v68
	v_mul_f32_e32 v45, v45, v68
	v_mul_f32_e32 v46, v46, v68
	v_mul_f32_e32 v47, v47, v68
	v_cvt_pk_bf16_f32 v40, v40, v41
	v_cvt_pk_bf16_f32 v41, v42, v43
	v_cvt_pk_bf16_f32 v42, v44, v45
	v_cvt_pk_bf16_f32 v43, v46, v47
	s_nop 1
	v_permlane32_swap_b32_e32 v40, v42
	v_permlane32_swap_b32_e32 v41, v43
	global_store_dwordx4 v[76:77], v[40:43], off offset:96
	v_mul_f32_e32 v16, v16, v70
	v_mul_f32_e32 v17, v17, v70
	v_mul_f32_e32 v18, v18, v70
	v_mul_f32_e32 v19, v19, v70
	v_mul_f32_e32 v20, v20, v70
	v_mul_f32_e32 v21, v21, v70
	v_mul_f32_e32 v22, v22, v70
	v_mul_f32_e32 v23, v23, v70
	v_cvt_pk_bf16_f32 v16, v16, v17
	v_cvt_pk_bf16_f32 v17, v18, v19
	v_cvt_pk_bf16_f32 v18, v20, v21
	v_cvt_pk_bf16_f32 v19, v22, v23
	s_nop 1
	v_permlane32_swap_b32_e32 v16, v18
	v_permlane32_swap_b32_e32 v17, v19
	global_store_dwordx4 v[78:79], v[16:19], off
	v_mul_f32_e32 v24, v24, v70
	v_mul_f32_e32 v25, v25, v70
	v_mul_f32_e32 v26, v26, v70
	v_mul_f32_e32 v27, v27, v70
	v_mul_f32_e32 v28, v28, v70
	v_mul_f32_e32 v29, v29, v70
	v_mul_f32_e32 v30, v30, v70
	v_mul_f32_e32 v31, v31, v70
	v_cvt_pk_bf16_f32 v24, v24, v25
	v_cvt_pk_bf16_f32 v25, v26, v27
	v_cvt_pk_bf16_f32 v26, v28, v29
	v_cvt_pk_bf16_f32 v27, v30, v31
	s_nop 1
	v_permlane32_swap_b32_e32 v24, v26
	v_permlane32_swap_b32_e32 v25, v27
	global_store_dwordx4 v[78:79], v[24:27], off offset:32
	v_mul_f32_e32 v0, v0, v70
	v_mul_f32_e32 v1, v1, v70
	v_mul_f32_e32 v2, v2, v70
	v_mul_f32_e32 v3, v3, v70
	v_mul_f32_e32 v4, v4, v70
	v_mul_f32_e32 v5, v5, v70
	v_mul_f32_e32 v6, v6, v70
	v_mul_f32_e32 v7, v7, v70
	v_cvt_pk_bf16_f32 v0, v0, v1
	v_cvt_pk_bf16_f32 v1, v2, v3
	v_cvt_pk_bf16_f32 v2, v4, v5
	v_cvt_pk_bf16_f32 v3, v6, v7
	s_nop 1
	v_permlane32_swap_b32_e32 v0, v2
	v_permlane32_swap_b32_e32 v1, v3
	global_store_dwordx4 v[78:79], v[0:3], off offset:64
	v_mul_f32_e32 v8, v8, v70
	v_mul_f32_e32 v9, v9, v70
	v_mul_f32_e32 v10, v10, v70
	v_mul_f32_e32 v11, v11, v70
	v_mul_f32_e32 v12, v12, v70
	v_mul_f32_e32 v13, v13, v70
	v_mul_f32_e32 v14, v14, v70
	v_mul_f32_e32 v15, v15, v70
	v_cvt_pk_bf16_f32 v8, v8, v9
	v_cvt_pk_bf16_f32 v9, v10, v11
	v_cvt_pk_bf16_f32 v10, v12, v13
	v_cvt_pk_bf16_f32 v11, v14, v15
	s_nop 1
	v_permlane32_swap_b32_e32 v8, v10
	v_permlane32_swap_b32_e32 v9, v11
	global_store_dwordx4 v[78:79], v[8:11], off offset:96
	v_readlane_b32 s0, v251, 20
	s_add_i32 s8, s8, s78
	s_add_i32 s2, s2, s0
	s_cmpk_gt_i32 s8, 0x1ff
	v_readlane_b32 s1, v251, 21
	s_cbranch_scc1 .LBB0_451

; template <bool FOX> ...
;     ...
; #pragma unroll
;   for (int qt = 0; qt < 2; ++qt) {
;     float lt = xsum32(lrun[qt]);
;     float inv = 1.f / lt;
;     u16* yp = Yb + (size_t)(q0 + qt * 32 + ln) * ldy;
; #pragma unroll
;     for (int dt = 0; dt < 2; ++dt)
; #pragma unroll
;       for (int jj = 0; jj < 4; ++jj) {
;         uint2 pk;
;         pk.x = pack2(o[dt][qt][4 * jj + 0] * inv, o[dt][qt][4 * jj + 1] * inv);
;         pk.y = pack2(o[dt][qt][4 * jj + 2] * inv, o[dt][qt][4 * jj + 3] * inv);
;         *reinterpret_cast<uint2*>(yp + dt * 32 + 8 * jj + 4 * hh) = pk;
;       }
;   }
.LBB0_505:
	s_lshl_b32 s5, s5, 10
	s_sub_u32 s5, 0, s5
	s_subb_u32 s7, 0, 0
	s_add_u32 s2, s2, s5
	s_addc_u32 s5, s4, s7
	s_lshl_b32 s4, s6, 1
	s_add_u32 s4, s2, s4
	s_addc_u32 s5, s5, 0
	v_mov_b32_e32 v66, v188
	v_mov_b32_e32 v67, v189
	s_nop 1
	v_permlane32_swap_b32_e32 v188, v66
	v_permlane32_swap_b32_e32 v189, v67
	v_lshl_add_u64 v[64:65], v[186:187], 1, s[4:5]
	s_mov_b64 s[4:5], 0xe840400
	v_add_f32_e32 v66, v188, v66
	v_add_f32_e32 v67, v189, v67
	v_lshl_add_u64 v[64:65], v[64:65], 0, s[4:5]
	v_div_scale_f32 v80, s[4:5], v66, v66, 1.0
	v_rcp_f32_e32 v81, v80
	v_div_scale_f32 v82, vcc, 1.0, v66, 1.0
	v_fma_f32 v83, -v80, v81, 1.0
	v_fmac_f32_e32 v81, v83, v81
	v_mul_f32_e32 v83, v82, v81
	v_fma_f32 v84, -v80, v83, v82
	v_fmac_f32_e32 v83, v84, v81
	v_fma_f32 v80, -v80, v83, v82
	v_div_fmas_f32 v80, v80, v81, v83
	v_div_fixup_f32 v68, v80, v66, 1.0
	v_div_scale_f32 v86, s[4:5], v67, v67, 1.0
	v_rcp_f32_e32 v87, v86
	v_div_scale_f32 v88, vcc, 1.0, v67, 1.0
	v_fma_f32 v89, -v86, v87, 1.0
	v_fmac_f32_e32 v87, v89, v87
	v_mul_f32_e32 v89, v88, v87
	v_fma_f32 v90, -v86, v89, v88
	v_fmac_f32_e32 v89, v90, v87
	v_fma_f32 v86, -v86, v89, v88
	v_div_fmas_f32 v86, v86, v87, v89
	v_div_fixup_f32 v70, v86, v67, 1.0
	v_mbcnt_lo_u32_b32 v74, -1, 0
	v_mbcnt_hi_u32_b32 v74, -1, v74
	v_and_b32_e32 v74, 32, v74
	v_lshrrev_b32_e32 v74, 2, v74
	v_mov_b32_e32 v75, 0
	v_lshlrev_b64 v[76:77], 11, v[180:181]
	v_lshlrev_b64 v[78:79], 11, v[178:179]
	v_lshl_add_u64 v[76:77], v[64:65], 0, v[76:77]
	v_lshl_add_u64 v[78:79], v[64:65], 0, v[78:79]
	v_lshl_add_u64 v[76:77], v[76:77], 0, v[74:75]
	v_lshl_add_u64 v[78:79], v[78:79], 0, v[74:75]
	v_mul_f32_e32 v48, v48, v68
	v_mul_f32_e32 v49, v49, v68
	v_mul_f32_e32 v50, v50, v68
	v_mul_f32_e32 v51, v51, v68
	v_mul_f32_e32 v52, v52, v68
	v_mul_f32_e32 v53, v53, v68
	v_mul_f32_e32 v54, v54, v68
	v_mul_f32_e32 v55, v55, v68
	v_cvt_pk_bf16_f32 v48, v48, v49
	v_cvt_pk_bf16_f32 v49, v50, v51
	v_cvt_pk_bf16_f32 v50, v52, v53
	v_cvt_pk_bf16_f32 v51, v54, v55
	s_nop 1
	v_permlane32_swap_b32_e32 v48, v50
	v_permlane32_swap_b32_e32 v49, v51
	global_store_dwordx4 v[76:77], v[48:51], off
	v_mul_f32_e32 v56, v56, v68
	v_mul_f32_e32 v57, v57, v68
	v_mul_f32_e32 v58, v58, v68
	v_mul_f32_e32 v59, v59, v68
	v_mul_f32_e32 v60, v60, v68
	v_mul_f32_e32 v61, v61, v68
	v_mul_f32_e32 v62, v62, v68
	v_mul_f32_e32 v63, v63, v68
	v_cvt_pk_bf16_f32 v56, v56, v57
	v_cvt_pk_bf16_f32 v57, v58, v59
	v_cvt_pk_bf16_f32 v58, v60, v61
	v_cvt_pk_bf16_f32 v59, v62, v63
	s_nop 1
	v_permlane32_swap_b32_e32 v56, v58
	v_permlane32_swap_b32_e32 v57, v59
	global_store_dwordx4 v[76:77], v[56:59], off offset:32
	v_mul_f32_e32 v32, v32, v68
	v_mul_f32_e32 v33, v33, v68
	v_mul_f32_e32 v34, v34, v68
	v_mul_f32_e32 v35, v35, v68
	v_mul_f32_e32 v36, v36, v68
	v_mul_f32_e32 v37, v37, v68
	v_mul_f32_e32 v38, v38, v68
	v_mul_f32_e32 v39, v39, v68
	v_cvt_pk_bf16_f32 v32, v32, v33
	v_cvt_pk_bf16_f32 v33, v34, v35
	v_cvt_pk_bf16_f32 v34, v36, v37
	v_cvt_pk_bf16_f32 v35, v38, v39
	s_nop 1
	v_permlane32_swap_b32_e32 v32, v34
	v_permlane32_swap_b32_e32 v33, v35
	global_store_dwordx4 v[76:77], v[32:35], off offset:64
	v_mul_f32_e32 v40, v40, v68
	v_mul_f32_e32 v41, v41, v68
	v_mul_f32_e32 v42, v42, v68
	v_mul_f32_e32 v43, v43, v68
	v_mul_f32_e32 v44, v44, v68
	v_mul_f32_e32 v45, v45, v68
	v_mul_f32_e32 v46, v46, v68
	v_mul_f32_e32 v47, v47, v68
	v_cvt_pk_bf16_f32 v40, v40, v41
	v_cvt_pk_bf16_f32 v41, v42, v43
	v_cvt_pk_bf16_f32 v42, v44, v45
	v_cvt_pk_bf16_f32 v43, v46, v47
	s_nop 1
	v_permlane32_swap_b32_e32 v40, v42
	v_permlane32_swap_b32_e32 v41, v43
	global_store_dwordx4 v[76:77], v[40:43], off offset:96
	v_mul_f32_e32 v16, v16, v70
	v_mul_f32_e32 v17, v17, v70
	v_mul_f32_e32 v18, v18, v70
	v_mul_f32_e32 v19, v19, v70
	v_mul_f32_e32 v20, v20, v70
	v_mul_f32_e32 v21, v21, v70
	v_mul_f32_e32 v22, v22, v70
	v_mul_f32_e32 v23, v23, v70
	v_cvt_pk_bf16_f32 v16, v16, v17
	v_cvt_pk_bf16_f32 v17, v18, v19
	v_cvt_pk_bf16_f32 v18, v20, v21
	v_cvt_pk_bf16_f32 v19, v22, v23
	s_nop 1
	v_permlane32_swap_b32_e32 v16, v18
	v_permlane32_swap_b32_e32 v17, v19
	global_store_dwordx4 v[78:79], v[16:19], off
	v_mul_f32_e32 v24, v24, v70
	v_mul_f32_e32 v25, v25, v70
	v_mul_f32_e32 v26, v26, v70
	v_mul_f32_e32 v27, v27, v70
	v_mul_f32_e32 v28, v28, v70
	v_mul_f32_e32 v29, v29, v70
	v_mul_f32_e32 v30, v30, v70
	v_mul_f32_e32 v31, v31, v70
	v_cvt_pk_bf16_f32 v24, v24, v25
	v_cvt_pk_bf16_f32 v25, v26, v27
	v_cvt_pk_bf16_f32 v26, v28, v29
	v_cvt_pk_bf16_f32 v27, v30, v31
	s_nop 1
	v_permlane32_swap_b32_e32 v24, v26
	v_permlane32_swap_b32_e32 v25, v27
	global_store_dwordx4 v[78:79], v[24:27], off offset:32
	v_mul_f32_e32 v0, v0, v70
	v_mul_f32_e32 v1, v1, v70
	v_mul_f32_e32 v2, v2, v70
	v_mul_f32_e32 v3, v3, v70
	v_mul_f32_e32 v4, v4, v70
	v_mul_f32_e32 v5, v5, v70
	v_mul_f32_e32 v6, v6, v70
	v_mul_f32_e32 v7, v7, v70
	v_cvt_pk_bf16_f32 v0, v0, v1
	v_cvt_pk_bf16_f32 v1, v2, v3
	v_cvt_pk_bf16_f32 v2, v4, v5
	v_cvt_pk_bf16_f32 v3, v6, v7
	s_nop 1
	v_permlane32_swap_b32_e32 v0, v2
	v_permlane32_swap_b32_e32 v1, v3
	global_store_dwordx4 v[78:79], v[0:3], off offset:64
	v_mul_f32_e32 v8, v8, v70
	v_mul_f32_e32 v9, v9, v70
	v_mul_f32_e32 v10, v10, v70
	v_mul_f32_e32 v11, v11, v70
	v_mul_f32_e32 v12, v12, v70
	v_mul_f32_e32 v13, v13, v70
	v_mul_f32_e32 v14, v14, v70
	v_mul_f32_e32 v15, v15, v70
	v_cvt_pk_bf16_f32 v8, v8, v9
	v_cvt_pk_bf16_f32 v9, v10, v11
	v_cvt_pk_bf16_f32 v10, v12, v13
	v_cvt_pk_bf16_f32 v11, v14, v15
	s_nop 1
	v_permlane32_swap_b32_e32 v8, v10
	v_permlane32_swap_b32_e32 v9, v11
	global_store_dwordx4 v[78:79], v[8:11], off offset:96
	s_add_i32 s1, s1, s78
	s_add_i32 s0, s0, s78
	s_cmpk_gt_i32 s1, 0x1ff
	s_cbranch_scc1 .LBB0_443
